# v29: v25 + final f32 y stores marked nt (streaming; less dirty L2 left for the end-of-kernel flush)
# baseline (speedup 1.0000x reference)
; __device__ __forceinline__ v4u pack8(const float (&f)[8]) { v4u w; w.x = pg8::cvt_pk_bf16(f[0], f[1]); w.y = pg8::cvt_pk_bf16(f[2], f[3]); w.z = pg8::cvt_pk_bf16(f[4], f[5]); w.w = pg8::cvt_pk_bf16(f[6], f[7]); return w; }
; __device__ __forceinline__ void ew_finish(const EwRow& r, const float (&gg)[2][8], float* __restrict__ Xrow32, bf16* __restrict__ Xrow16, bool dst16, float* __restrict__ rsp, bool write_xn, int lane) {
;     ...
;     if (dst16) { v4u* Xr = (v4u*)Xrow16 + lane;
; #pragma unroll
;         for (int j = 0; j < 2; ++j) Xr[64 * j] = pack8(x[j]); }
;     else { f32x4* Xr = (f32x4*)Xrow32 + 2 * lane;
; #pragma unroll
;         for (int j = 0; j < 2; ++j) { Xr[128 * j] = (f32x4){x[j][0], x[j][1], x[j][2], x[j][3]}; Xr[128 * j + 1] = (f32x4){x[j][4], x[j][5], x[j][6], x[j][7]}; } }
.LBB0_441:
	global_store_dwordx4 v68, v[48:51], s[12:13] nt
	global_store_dwordx4 v68, v[52:55], s[12:13] offset:16 nt
	global_store_dwordx4 v68, v[56:59], s[12:13] offset:2048 nt
	global_store_dwordx4 v68, v[60:63], s[12:13] offset:2064 nt
	s_cbranch_execnz .LBB0_440
